# L2 tile: first step's coefficient loads issued inside the carry-in (one exposed latency fewer)
# speedup vs baseline: 1.0149x; 1.0021x over previous
.Ll2ci_skip_0_4:
	s_mov_b64 exec, s[26:27]
	s_mov_b64 exec, s[58:59]
	global_load_dwordx4 v[208:211], v100, s[76:77] offset:0
	global_load_dwordx4 v[224:227], v100, s[78:79] offset:0
	global_load_dwordx4 v[212:215], v100, s[76:77] offset:64
	global_load_dwordx4 v[234:237], v100, s[78:79] offset:64
	global_load_dwordx4 v[216:219], v100, s[76:77] offset:128
	global_load_dwordx4 v[246:249], v100, s[78:79] offset:128
	global_load_dwordx4 v[220:223], v100, s[76:77] offset:192
	global_load_dwordx4 v[250:253], v100, s[78:79] offset:192
	s_mov_b64 exec, s[26:27]
	s_nop 4
	v_fmac_f32_dpp v2, v2, v56 row_shr:1 row_mask:0xf bank_mask:0xf bound_ctrl:1
	v_mul_f32_dpp v56, v56, v56 row_shr:1 row_mask:0xf bank_mask:0xf
	v_fmac_f32_dpp v3, v3, v57 row_shr:1 row_mask:0xf bank_mask:0xf bound_ctrl:1
	v_mul_f32_dpp v57, v57, v57 row_shr:1 row_mask:0xf bank_mask:0xf
	v_fmac_f32_dpp v4, v4, v58 row_shr:1 row_mask:0xf bank_mask:0xf bound_ctrl:1
	v_mul_f32_dpp v58, v58, v58 row_shr:1 row_mask:0xf bank_mask:0xf
	v_fmac_f32_dpp v5, v5, v59 row_shr:1 row_mask:0xf bank_mask:0xf bound_ctrl:1
	v_mul_f32_dpp v59, v59, v59 row_shr:1 row_mask:0xf bank_mask:0xf
	v_fmac_f32_dpp v6, v6, v60 row_shr:1 row_mask:0xf bank_mask:0xf bound_ctrl:1
	v_mul_f32_dpp v60, v60, v60 row_shr:1 row_mask:0xf bank_mask:0xf
	v_fmac_f32_dpp v7, v7, v61 row_shr:1 row_mask:0xf bank_mask:0xf bound_ctrl:1
	v_mul_f32_dpp v61, v61, v61 row_shr:1 row_mask:0xf bank_mask:0xf
	v_fmac_f32_dpp v8, v8, v62 row_shr:1 row_mask:0xf bank_mask:0xf bound_ctrl:1
	v_mul_f32_dpp v62, v62, v62 row_shr:1 row_mask:0xf bank_mask:0xf
	v_fmac_f32_dpp v9, v9, v63 row_shr:1 row_mask:0xf bank_mask:0xf bound_ctrl:1
	v_mul_f32_dpp v63, v63, v63 row_shr:1 row_mask:0xf bank_mask:0xf
	v_fmac_f32_dpp v10, v10, v64 row_shr:1 row_mask:0xf bank_mask:0xf bound_ctrl:1
	v_mul_f32_dpp v64, v64, v64 row_shr:1 row_mask:0xf bank_mask:0xf
	v_fmac_f32_dpp v11, v11, v65 row_shr:1 row_mask:0xf bank_mask:0xf bound_ctrl:1
	v_mul_f32_dpp v65, v65, v65 row_shr:1 row_mask:0xf bank_mask:0xf
	v_fmac_f32_dpp v12, v12, v66 row_shr:1 row_mask:0xf bank_mask:0xf bound_ctrl:1
	v_mul_f32_dpp v66, v66, v66 row_shr:1 row_mask:0xf bank_mask:0xf
	v_fmac_f32_dpp v13, v13, v67 row_shr:1 row_mask:0xf bank_mask:0xf bound_ctrl:1
	v_mul_f32_dpp v67, v67, v67 row_shr:1 row_mask:0xf bank_mask:0xf
	v_fmac_f32_dpp v14, v14, v68 row_shr:1 row_mask:0xf bank_mask:0xf bound_ctrl:1
	v_mul_f32_dpp v68, v68, v68 row_shr:1 row_mask:0xf bank_mask:0xf
	v_fmac_f32_dpp v15, v15, v69 row_shr:1 row_mask:0xf bank_mask:0xf bound_ctrl:1
	v_mul_f32_dpp v69, v69, v69 row_shr:1 row_mask:0xf bank_mask:0xf
	v_fmac_f32_dpp v16, v16, v70 row_shr:1 row_mask:0xf bank_mask:0xf bound_ctrl:1
	v_mul_f32_dpp v70, v70, v70 row_shr:1 row_mask:0xf bank_mask:0xf
	v_fmac_f32_dpp v17, v17, v71 row_shr:1 row_mask:0xf bank_mask:0xf bound_ctrl:1
	v_mul_f32_dpp v71, v71, v71 row_shr:1 row_mask:0xf bank_mask:0xf
	v_fmac_f32_dpp v2, v2, v56 row_shr:2 row_mask:0xf bank_mask:0xf bound_ctrl:1
	v_mul_f32_dpp v56, v56, v56 row_shr:2 row_mask:0xf bank_mask:0xf
	v_fmac_f32_dpp v3, v3, v57 row_shr:2 row_mask:0xf bank_mask:0xf bound_ctrl:1
	v_mul_f32_dpp v57, v57, v57 row_shr:2 row_mask:0xf bank_mask:0xf
	v_fmac_f32_dpp v4, v4, v58 row_shr:2 row_mask:0xf bank_mask:0xf bound_ctrl:1
	v_mul_f32_dpp v58, v58, v58 row_shr:2 row_mask:0xf bank_mask:0xf
	v_fmac_f32_dpp v5, v5, v59 row_shr:2 row_mask:0xf bank_mask:0xf bound_ctrl:1
	v_mul_f32_dpp v59, v59, v59 row_shr:2 row_mask:0xf bank_mask:0xf
	v_fmac_f32_dpp v6, v6, v60 row_shr:2 row_mask:0xf bank_mask:0xf bound_ctrl:1
	v_mul_f32_dpp v60, v60, v60 row_shr:2 row_mask:0xf bank_mask:0xf
	v_fmac_f32_dpp v7, v7, v61 row_shr:2 row_mask:0xf bank_mask:0xf bound_ctrl:1
	v_mul_f32_dpp v61, v61, v61 row_shr:2 row_mask:0xf bank_mask:0xf
	v_fmac_f32_dpp v8, v8, v62 row_shr:2 row_mask:0xf bank_mask:0xf bound_ctrl:1
	v_mul_f32_dpp v62, v62, v62 row_shr:2 row_mask:0xf bank_mask:0xf
	v_fmac_f32_dpp v9, v9, v63 row_shr:2 row_mask:0xf bank_mask:0xf bound_ctrl:1
	v_mul_f32_dpp v63, v63, v63 row_shr:2 row_mask:0xf bank_mask:0xf
	v_fmac_f32_dpp v10, v10, v64 row_shr:2 row_mask:0xf bank_mask:0xf bound_ctrl:1
	v_mul_f32_dpp v64, v64, v64 row_shr:2 row_mask:0xf bank_mask:0xf
	v_fmac_f32_dpp v11, v11, v65 row_shr:2 row_mask:0xf bank_mask:0xf bound_ctrl:1
	v_mul_f32_dpp v65, v65, v65 row_shr:2 row_mask:0xf bank_mask:0xf
	v_fmac_f32_dpp v12, v12, v66 row_shr:2 row_mask:0xf bank_mask:0xf bound_ctrl:1
	v_mul_f32_dpp v66, v66, v66 row_shr:2 row_mask:0xf bank_mask:0xf
	v_fmac_f32_dpp v13, v13, v67 row_shr:2 row_mask:0xf bank_mask:0xf bound_ctrl:1
	v_mul_f32_dpp v67, v67, v67 row_shr:2 row_mask:0xf bank_mask:0xf
	v_fmac_f32_dpp v14, v14, v68 row_shr:2 row_mask:0xf bank_mask:0xf bound_ctrl:1
	v_mul_f32_dpp v68, v68, v68 row_shr:2 row_mask:0xf bank_mask:0xf
	v_fmac_f32_dpp v15, v15, v69 row_shr:2 row_mask:0xf bank_mask:0xf bound_ctrl:1
	v_mul_f32_dpp v69, v69, v69 row_shr:2 row_mask:0xf bank_mask:0xf
	v_fmac_f32_dpp v16, v16, v70 row_shr:2 row_mask:0xf bank_mask:0xf bound_ctrl:1
	v_mul_f32_dpp v70, v70, v70 row_shr:2 row_mask:0xf bank_mask:0xf
	v_fmac_f32_dpp v17, v17, v71 row_shr:2 row_mask:0xf bank_mask:0xf bound_ctrl:1
	v_mul_f32_dpp v71, v71, v71 row_shr:2 row_mask:0xf bank_mask:0xf
	v_fmac_f32_dpp v2, v2, v56 row_shr:4 row_mask:0xf bank_mask:0xf bound_ctrl:1
	v_mul_f32_dpp v56, v56, v56 row_shr:4 row_mask:0xf bank_mask:0xf
	v_fmac_f32_dpp v3, v3, v57 row_shr:4 row_mask:0xf bank_mask:0xf bound_ctrl:1
	v_mul_f32_dpp v57, v57, v57 row_shr:4 row_mask:0xf bank_mask:0xf
	v_fmac_f32_dpp v4, v4, v58 row_shr:4 row_mask:0xf bank_mask:0xf bound_ctrl:1
	v_mul_f32_dpp v58, v58, v58 row_shr:4 row_mask:0xf bank_mask:0xf
	v_fmac_f32_dpp v5, v5, v59 row_shr:4 row_mask:0xf bank_mask:0xf bound_ctrl:1
	v_mul_f32_dpp v59, v59, v59 row_shr:4 row_mask:0xf bank_mask:0xf
	v_fmac_f32_dpp v6, v6, v60 row_shr:4 row_mask:0xf bank_mask:0xf bound_ctrl:1
	v_mul_f32_dpp v60, v60, v60 row_shr:4 row_mask:0xf bank_mask:0xf
	v_fmac_f32_dpp v7, v7, v61 row_shr:4 row_mask:0xf bank_mask:0xf bound_ctrl:1
	v_mul_f32_dpp v61, v61, v61 row_shr:4 row_mask:0xf bank_mask:0xf
	v_fmac_f32_dpp v8, v8, v62 row_shr:4 row_mask:0xf bank_mask:0xf bound_ctrl:1
	v_mul_f32_dpp v62, v62, v62 row_shr:4 row_mask:0xf bank_mask:0xf
	v_fmac_f32_dpp v9, v9, v63 row_shr:4 row_mask:0xf bank_mask:0xf bound_ctrl:1
	v_mul_f32_dpp v63, v63, v63 row_shr:4 row_mask:0xf bank_mask:0xf
	v_fmac_f32_dpp v10, v10, v64 row_shr:4 row_mask:0xf bank_mask:0xf bound_ctrl:1
	v_mul_f32_dpp v64, v64, v64 row_shr:4 row_mask:0xf bank_mask:0xf
	v_fmac_f32_dpp v11, v11, v65 row_shr:4 row_mask:0xf bank_mask:0xf bound_ctrl:1
	v_mul_f32_dpp v65, v65, v65 row_shr:4 row_mask:0xf bank_mask:0xf
	v_fmac_f32_dpp v12, v12, v66 row_shr:4 row_mask:0xf bank_mask:0xf bound_ctrl:1
	v_mul_f32_dpp v66, v66, v66 row_shr:4 row_mask:0xf bank_mask:0xf
	v_fmac_f32_dpp v13, v13, v67 row_shr:4 row_mask:0xf bank_mask:0xf bound_ctrl:1
	v_mul_f32_dpp v67, v67, v67 row_shr:4 row_mask:0xf bank_mask:0xf
	v_fmac_f32_dpp v14, v14, v68 row_shr:4 row_mask:0xf bank_mask:0xf bound_ctrl:1
	v_mul_f32_dpp v68, v68, v68 row_shr:4 row_mask:0xf bank_mask:0xf
	v_fmac_f32_dpp v15, v15, v69 row_shr:4 row_mask:0xf bank_mask:0xf bound_ctrl:1
	v_mul_f32_dpp v69, v69, v69 row_shr:4 row_mask:0xf bank_mask:0xf
	v_fmac_f32_dpp v16, v16, v70 row_shr:4 row_mask:0xf bank_mask:0xf bound_ctrl:1
	v_mul_f32_dpp v70, v70, v70 row_shr:4 row_mask:0xf bank_mask:0xf
	v_fmac_f32_dpp v17, v17, v71 row_shr:4 row_mask:0xf bank_mask:0xf bound_ctrl:1
	v_mul_f32_dpp v71, v71, v71 row_shr:4 row_mask:0xf bank_mask:0xf
	v_fmac_f32_dpp v2, v2, v56 row_shr:8 row_mask:0xf bank_mask:0xf bound_ctrl:1
	v_fmac_f32_dpp v3, v3, v57 row_shr:8 row_mask:0xf bank_mask:0xf bound_ctrl:1
	v_fmac_f32_dpp v4, v4, v58 row_shr:8 row_mask:0xf bank_mask:0xf bound_ctrl:1
	v_fmac_f32_dpp v5, v5, v59 row_shr:8 row_mask:0xf bank_mask:0xf bound_ctrl:1
	v_fmac_f32_dpp v6, v6, v60 row_shr:8 row_mask:0xf bank_mask:0xf bound_ctrl:1
	v_fmac_f32_dpp v7, v7, v61 row_shr:8 row_mask:0xf bank_mask:0xf bound_ctrl:1
	v_fmac_f32_dpp v8, v8, v62 row_shr:8 row_mask:0xf bank_mask:0xf bound_ctrl:1
	v_fmac_f32_dpp v9, v9, v63 row_shr:8 row_mask:0xf bank_mask:0xf bound_ctrl:1
	v_fmac_f32_dpp v10, v10, v64 row_shr:8 row_mask:0xf bank_mask:0xf bound_ctrl:1
	v_fmac_f32_dpp v11, v11, v65 row_shr:8 row_mask:0xf bank_mask:0xf bound_ctrl:1
	v_fmac_f32_dpp v12, v12, v66 row_shr:8 row_mask:0xf bank_mask:0xf bound_ctrl:1
	v_fmac_f32_dpp v13, v13, v67 row_shr:8 row_mask:0xf bank_mask:0xf bound_ctrl:1
	v_fmac_f32_dpp v14, v14, v68 row_shr:8 row_mask:0xf bank_mask:0xf bound_ctrl:1
	v_fmac_f32_dpp v15, v15, v69 row_shr:8 row_mask:0xf bank_mask:0xf bound_ctrl:1
	v_fmac_f32_dpp v16, v16, v70 row_shr:8 row_mask:0xf bank_mask:0xf bound_ctrl:1
	v_fmac_f32_dpp v17, v17, v71 row_shr:8 row_mask:0xf bank_mask:0xf bound_ctrl:1
	s_nop 1
	ds_bpermute_b32 v34, v245, v2
	ds_bpermute_b32 v35, v245, v3
	ds_bpermute_b32 v32, v245, v4
	ds_bpermute_b32 v33, v245, v5
	ds_bpermute_b32 v30, v245, v6
	ds_bpermute_b32 v31, v245, v7
	ds_bpermute_b32 v28, v245, v8
	ds_bpermute_b32 v29, v245, v9
	ds_bpermute_b32 v26, v245, v10
	ds_bpermute_b32 v27, v245, v11
	ds_bpermute_b32 v24, v245, v12
	ds_bpermute_b32 v25, v245, v13
	ds_bpermute_b32 v22, v245, v14
	ds_bpermute_b32 v23, v245, v15
	ds_bpermute_b32 v20, v245, v16
	ds_bpermute_b32 v21, v245, v17
	s_waitcnt vmcnt(32)
	v_cndmask_b32_e64 v56, 1.0, v36, s[18:19]
	v_cndmask_b32_e64 v2, 0, v84, s[18:19]
	v_cndmask_b32_e64 v57, 1.0, v37, s[18:19]
	v_cndmask_b32_e64 v3, 0, v85, s[18:19]
	v_cndmask_b32_e64 v58, 1.0, v38, s[18:19]
	v_cndmask_b32_e64 v4, 0, v86, s[18:19]
	v_cndmask_b32_e64 v59, 1.0, v39, s[18:19]
	v_cndmask_b32_e64 v5, 0, v87, s[18:19]
	v_cndmask_b32_e64 v60, 1.0, v40, s[18:19]
	v_cndmask_b32_e64 v6, 0, v88, s[18:19]
	v_cndmask_b32_e64 v61, 1.0, v41, s[18:19]
	v_cndmask_b32_e64 v7, 0, v89, s[18:19]
	v_cndmask_b32_e64 v62, 1.0, v42, s[18:19]
	v_cndmask_b32_e64 v8, 0, v90, s[18:19]
	v_cndmask_b32_e64 v63, 1.0, v43, s[18:19]
	v_cndmask_b32_e64 v9, 0, v91, s[18:19]
	v_cndmask_b32_e64 v64, 1.0, v44, s[18:19]
	v_cndmask_b32_e64 v10, 0, v102, s[18:19]
	v_cndmask_b32_e64 v65, 1.0, v45, s[18:19]
	v_cndmask_b32_e64 v11, 0, v103, s[18:19]
	v_cndmask_b32_e64 v66, 1.0, v46, s[18:19]
	v_cndmask_b32_e64 v12, 0, v104, s[18:19]
	v_cndmask_b32_e64 v67, 1.0, v47, s[18:19]
	v_cndmask_b32_e64 v13, 0, v105, s[18:19]
	v_cndmask_b32_e64 v68, 1.0, v48, s[18:19]
	v_cndmask_b32_e64 v14, 0, v106, s[18:19]
	v_cndmask_b32_e64 v69, 1.0, v49, s[18:19]
	v_cndmask_b32_e64 v15, 0, v107, s[18:19]
	v_cndmask_b32_e64 v70, 1.0, v50, s[18:19]
	v_cndmask_b32_e64 v16, 0, v108, s[18:19]
	v_cndmask_b32_e64 v71, 1.0, v51, s[18:19]
	v_cndmask_b32_e64 v17, 0, v109, s[18:19]
	s_lshl_b32 s10, s48, 6
	s_add_i32 s11, s10, 0xffffff00
	s_and_b64 s[8:9], s[6:7], exec
	s_cselect_b32 s8, s11, s10
	s_lshl_b32 s9, s40, 8
	s_addk_i32 s9, 0x4000
	s_lshl_b32 s10, s40, 12
	s_and_b64 s[6:7], s[6:7], exec
	s_cselect_b32 s10, s10, s9
	s_add_i32 s10, s10, s8
	s_ashr_i32 s6, s10, 4
	s_ashr_i32 s7, s6, 31
	s_lshl_b64 s[8:9], s[6:7], 14
	s_add_u32 s8, s4, s8
	s_addc_u32 s9, s5, s9
	s_lshl_b64 s[6:7], s[6:7], 15
	v_lshlrev_b32_e32 v0, 5, v101
	s_add_u32 s6, s30, s6
	v_lshl_add_u64 v[54:55], s[8:9], 0, v[0:1]
	s_addc_u32 s7, s31, s7
	v_lshlrev_b32_e32 v0, 6, v101
	v_lshl_add_u64 v[94:95], s[6:7], 0, v[0:1]
	v_lshl_add_u64 v[52:53], v[18:19], 2, v[94:95]
	global_load_dwordx4 v[84:87], v[52:53], off
	global_load_dwordx4 v[88:91], v[52:53], off offset:1024
	global_load_dwordx4 v[102:105], v[52:53], off offset:2048
	global_load_dwordx4 v[106:109], v[52:53], off offset:3072
	s_waitcnt vmcnt(28)
	s_mov_b64 exec, s[20:21]
	s_cbranch_execz .Ll2ci_skip_1_1
	v_pk_fma_f32 v[2:3], v[110:111], v[2:3], v[126:127]
	v_pk_mul_f32 v[56:57], v[56:57], v[110:111]
	v_pk_fma_f32 v[4:5], v[112:113], v[4:5], v[128:129]
	v_pk_mul_f32 v[58:59], v[58:59], v[112:113]
	v_pk_fma_f32 v[6:7], v[114:115], v[6:7], v[130:131]
	v_pk_mul_f32 v[60:61], v[60:61], v[114:115]
	v_pk_fma_f32 v[8:9], v[116:117], v[8:9], v[132:133]
	v_pk_mul_f32 v[62:63], v[62:63], v[116:117]
	v_pk_fma_f32 v[10:11], v[118:119], v[10:11], v[134:135]
	v_pk_mul_f32 v[64:65], v[64:65], v[118:119]
	v_pk_fma_f32 v[12:13], v[120:121], v[12:13], v[136:137]
	v_pk_mul_f32 v[66:67], v[66:67], v[120:121]
	v_pk_fma_f32 v[14:15], v[122:123], v[14:15], v[138:139]
	v_pk_mul_f32 v[68:69], v[68:69], v[122:123]
	v_pk_fma_f32 v[16:17], v[124:125], v[16:17], v[140:141]
	v_pk_mul_f32 v[70:71], v[70:71], v[124:125]
.Ll2ci_skip_1_1:
	s_mov_b64 exec, s[26:27]
	s_waitcnt vmcnt(20)
	s_mov_b64 exec, s[22:23]
	s_cbranch_execz .Ll2ci_skip_1_2
	v_pk_fma_f32 v[2:3], v[142:143], v[2:3], v[158:159]
	v_pk_mul_f32 v[56:57], v[56:57], v[142:143]
	v_pk_fma_f32 v[4:5], v[144:145], v[4:5], v[160:161]
	v_pk_mul_f32 v[58:59], v[58:59], v[144:145]
	v_pk_fma_f32 v[6:7], v[146:147], v[6:7], v[162:163]
	v_pk_mul_f32 v[60:61], v[60:61], v[146:147]
	v_pk_fma_f32 v[8:9], v[148:149], v[8:9], v[164:165]
	v_pk_mul_f32 v[62:63], v[62:63], v[148:149]
	v_pk_fma_f32 v[10:11], v[150:151], v[10:11], v[166:167]
	v_pk_mul_f32 v[64:65], v[64:65], v[150:151]
	v_pk_fma_f32 v[12:13], v[152:153], v[12:13], v[168:169]
	v_pk_mul_f32 v[66:67], v[66:67], v[152:153]
	v_pk_fma_f32 v[14:15], v[154:155], v[14:15], v[170:171]
	v_pk_mul_f32 v[68:69], v[68:69], v[154:155]
	v_pk_fma_f32 v[16:17], v[156:157], v[16:17], v[172:173]
	v_pk_mul_f32 v[70:71], v[70:71], v[156:157]
.Ll2ci_skip_1_2:
	s_mov_b64 exec, s[26:27]
	s_waitcnt vmcnt(12)
	s_mov_b64 exec, s[24:25]
	s_cbranch_execz .Ll2ci_skip_1_3
	v_pk_fma_f32 v[2:3], v[174:175], v[2:3], v[192:193]
	v_pk_mul_f32 v[56:57], v[56:57], v[174:175]
	v_pk_fma_f32 v[4:5], v[176:177], v[4:5], v[194:195]
	v_pk_mul_f32 v[58:59], v[58:59], v[176:177]
	v_pk_fma_f32 v[6:7], v[178:179], v[6:7], v[196:197]
	v_pk_mul_f32 v[60:61], v[60:61], v[178:179]
	v_pk_fma_f32 v[8:9], v[180:181], v[8:9], v[198:199]
	v_pk_mul_f32 v[62:63], v[62:63], v[180:181]
	v_pk_fma_f32 v[10:11], v[182:183], v[10:11], v[200:201]
	v_pk_mul_f32 v[64:65], v[64:65], v[182:183]
	v_pk_fma_f32 v[12:13], v[184:185], v[12:13], v[202:203]
	v_pk_mul_f32 v[66:67], v[66:67], v[184:185]
	v_pk_fma_f32 v[14:15], v[186:187], v[14:15], v[204:205]
	v_pk_mul_f32 v[68:69], v[68:69], v[186:187]
	v_pk_fma_f32 v[16:17], v[188:189], v[16:17], v[206:207]
	v_pk_mul_f32 v[70:71], v[70:71], v[188:189]
.Ll2ci_skip_1_3:
	s_mov_b64 exec, s[26:27]
	s_waitcnt vmcnt(4)
	s_mov_b64 exec, s[58:59]
	s_cbranch_execz .Ll2ci_skip_1_4
	v_pk_fma_f32 v[2:3], v[208:209], v[2:3], v[224:225]
	v_pk_mul_f32 v[56:57], v[56:57], v[208:209]
	v_pk_fma_f32 v[4:5], v[210:211], v[4:5], v[226:227]
	v_pk_mul_f32 v[58:59], v[58:59], v[210:211]
	v_pk_fma_f32 v[6:7], v[212:213], v[6:7], v[234:235]
	v_pk_mul_f32 v[60:61], v[60:61], v[212:213]
	v_pk_fma_f32 v[8:9], v[214:215], v[8:9], v[236:237]
	v_pk_mul_f32 v[62:63], v[62:63], v[214:215]
	v_pk_fma_f32 v[10:11], v[216:217], v[10:11], v[246:247]
	v_pk_mul_f32 v[64:65], v[64:65], v[216:217]
	v_pk_fma_f32 v[12:13], v[218:219], v[12:13], v[248:249]
	v_pk_mul_f32 v[66:67], v[66:67], v[218:219]
	v_pk_fma_f32 v[14:15], v[220:221], v[14:15], v[250:251]
	v_pk_mul_f32 v[68:69], v[68:69], v[220:221]
	v_pk_fma_f32 v[16:17], v[222:223], v[16:17], v[252:253]
	v_pk_mul_f32 v[70:71], v[70:71], v[222:223]

.LBB0_279:
	v_xor_b32_e32 v0, 16, v228
	v_add_u32_e32 v123, 64, v82
	v_cmp_lt_i32_e32 vcc, v0, v123
	v_lshlrev_b32_e32 v124, 2, v97
	v_add_u32_e32 v125, s3, v124
	v_cndmask_b32_e32 v0, v228, v0, vcc
	v_lshlrev_b32_e32 v121, 2, v0
	v_xor_b32_e32 v0, 32, v228
	v_cmp_lt_i32_e32 vcc, v0, v123
	v_lshl_add_u64 v[54:55], v[18:19], 1, v[54:55]
	v_cmp_gt_u32_e64 s[6:7], 16, v97
	v_cndmask_b32_e32 v0, v228, v0, vcc
	v_lshlrev_b32_e32 v122, 2, v0
	v_add_u32_e32 v126, s46, v124
	s_mov_b32 s14, 0
	s_mov_b32 s11, 7
	v_mov_b32_e32 v160, 0
	v_mov_b32_e32 v159, 0
	v_mov_b32_e32 v162, 0
	v_mov_b32_e32 v161, 0
	v_mov_b32_e32 v114, 0
	v_mov_b32_e32 v163, 0
	v_mov_b32_e32 v118, 0
	v_mov_b32_e32 v116, 0
	s_branch .LBB0_281
.LBB0_281:
	s_waitcnt lgkmcnt(0)
	s_waitcnt vmcnt(0)
	v_mov_b64_e32 v[2:3], v[84:85]
	v_mov_b64_e32 v[4:5], v[86:87]
	v_mov_b64_e32 v[6:7], v[88:89]
	v_mov_b64_e32 v[8:9], v[90:91]
	v_mov_b64_e32 v[10:11], v[102:103]
	v_mov_b64_e32 v[12:13], v[104:105]
	v_mov_b64_e32 v[14:15], v[106:107]
	v_mov_b64_e32 v[16:17], v[108:109]
	v_mov_b64_e32 v[192:193], v[34:35]
	v_mov_b64_e32 v[194:195], v[32:33]
	v_mov_b64_e32 v[196:197], v[30:31]
	v_mov_b64_e32 v[198:199], v[28:29]
	v_mov_b64_e32 v[200:201], v[26:27]
	v_mov_b64_e32 v[202:203], v[24:25]
	v_mov_b64_e32 v[204:205], v[22:23]
	v_mov_b64_e32 v[206:207], v[20:21]
